# attention: L1 prefetch of the 4 dependent K/V staging groups per item (additive), on top of mix2 prefetch + LRU batch + tail overlap
# speedup vs baseline: 1.0083x; 1.0083x over previous
.LBB0_323:
	flat_load_dwordx2 v[102:103], v[96:97] offset:216
	flat_load_dwordx2 v[0:1], v[96:97] offset:112
	s_and_b32 s38, s3, 31
	s_ashr_i32 s34, s3, 6
	v_add_co_u32_e64 v14, s[22:23], s38, -1
	s_ashr_i32 s35, s34, 31
	v_ashrrev_i32_e32 v15, 31, v14
	s_bfe_u32 s39, s3, 0x10005
	s_lshl_b64 s[34:35], s[34:35], 12
	v_lshlrev_b64 v[14:15], 7, v[14:15]
	v_mov_b32_e32 v4, 0
	v_lshlrev_b32_e32 v16, 1, v84
	v_mov_b32_e32 v6, 0
	v_mov_b32_e32 v7, 0
	v_mov_b32_e32 v8, 0
	v_mov_b32_e32 v9, 0
	v_mov_b32_e32 v10, v2
	v_mov_b32_e32 v11, v2
	v_mov_b32_e32 v12, v2
	s_lshl_b32 s53, s39, 6
	s_or_b64 s[54:55], s[6:7], s[22:23]
	v_lshl_add_u64 v[18:19], v[14:15], 0, s[34:35]
	v_mov_b32_e32 v13, v2
	s_waitcnt vmcnt(0) lgkmcnt(0)
	v_lshl_add_u64 v[14:15], v[102:103], 0, s[28:29]
	s_lshl_b32 s100, s53, 1
	s_mov_b32 s101, 0
	v_mov_b32_e32 v250, v16
	v_mov_b32_e32 v251, v2
	v_lshl_add_u64 v[252:253], v[18:19], 0, v[86:87]
	v_mad_u64_u32 v[248:249], s[88:89], v252, s45, v[14:15]
	v_mad_i32_i24 v249, v253, s45, v249
	v_lshl_add_u64 v[248:249], v[248:249], 0, s[100:101]
	v_lshl_add_u64 v[248:249], v[248:249], 0, v[250:251]
	global_load_dwordx4 v[240:243], v[248:249], off offset:2048
	global_load_dwordx4 v[244:247], v[248:249], off offset:2304
	v_lshl_add_u64 v[252:253], v[18:19], 0, v[88:89]
	v_mad_u64_u32 v[248:249], s[88:89], v252, s45, v[14:15]
	v_mad_i32_i24 v249, v253, s45, v249
	v_lshl_add_u64 v[248:249], v[248:249], 0, s[100:101]
	v_lshl_add_u64 v[248:249], v[248:249], 0, v[250:251]
	global_load_dwordx4 v[240:243], v[248:249], off offset:2048
	global_load_dwordx4 v[244:247], v[248:249], off offset:2304
	v_lshl_add_u64 v[252:253], v[18:19], 0, v[90:91]
	v_mad_u64_u32 v[248:249], s[88:89], v252, s45, v[14:15]
	v_mad_i32_i24 v249, v253, s45, v249
	v_lshl_add_u64 v[248:249], v[248:249], 0, s[100:101]
	v_lshl_add_u64 v[248:249], v[248:249], 0, v[250:251]
	global_load_dwordx4 v[240:243], v[248:249], off offset:2048
	global_load_dwordx4 v[244:247], v[248:249], off offset:2304
	v_lshl_add_u64 v[252:253], v[18:19], 0, v[92:93]
	v_mad_u64_u32 v[248:249], s[88:89], v252, s45, v[14:15]
	v_mad_i32_i24 v249, v253, s45, v249
	v_lshl_add_u64 v[248:249], v[248:249], 0, s[100:101]
	v_lshl_add_u64 v[248:249], v[248:249], 0, v[250:251]
	global_load_dwordx4 v[240:243], v[248:249], off offset:2048
	global_load_dwordx4 v[244:247], v[248:249], off offset:2304
	s_and_saveexec_b64 s[36:37], s[54:55]
	s_cbranch_execz .LBB0_325
	v_lshl_add_u64 v[6:7], v[18:19], 0, v[86:87]
	v_mad_u64_u32 v[8:9], s[54:55], v6, s45, v[14:15]
	v_mad_i32_i24 v9, v7, s45, v9
	s_lshl_b32 s26, s53, 1
	v_lshl_add_u64 v[6:7], v[8:9], 0, s[26:27]
	v_mov_b32_e32 v17, v2
	v_lshl_add_u64 v[6:7], v[6:7], 0, v[16:17]
	global_load_dwordx4 v[10:13], v[6:7], off offset:2048
	s_nop 0
	global_load_dwordx4 v[6:9], v[6:7], off offset:2304

.LBB0_1060:
	flat_load_dwordx2 v[102:103], v[96:97] offset:216
	flat_load_dwordx2 v[0:1], v[96:97] offset:112
	s_and_b32 s40, s3, 31
	s_ashr_i32 s36, s3, 6
	v_add_co_u32_e64 v14, s[26:27], s40, -1
	s_ashr_i32 s37, s36, 31
	v_ashrrev_i32_e32 v15, 31, v14
	s_bfe_u32 s41, s3, 0x10005
	s_lshl_b64 s[36:37], s[36:37], 12
	v_lshlrev_b64 v[14:15], 7, v[14:15]
	v_mov_b32_e32 v4, 0
	v_lshlrev_b32_e32 v16, 1, v84
	v_mov_b32_e32 v6, 0
	v_mov_b32_e32 v7, 0
	v_mov_b32_e32 v8, 0
	v_mov_b32_e32 v9, 0
	v_mov_b32_e32 v10, v2
	v_mov_b32_e32 v11, v2
	v_mov_b32_e32 v12, v2
	s_lshl_b32 s51, s41, 6
	s_or_b64 s[52:53], s[8:9], s[26:27]
	v_lshl_add_u64 v[18:19], v[14:15], 0, s[36:37]
	v_mov_b32_e32 v13, v2
	s_waitcnt vmcnt(0) lgkmcnt(0)
	v_lshl_add_u64 v[14:15], v[102:103], 0, s[30:31]
	s_lshl_b32 s100, s51, 1
	s_mov_b32 s101, 0
	v_mov_b32_e32 v250, v16
	v_mov_b32_e32 v251, v2
	v_lshl_add_u64 v[252:253], v[18:19], 0, v[86:87]
	v_mad_u64_u32 v[248:249], s[88:89], v252, s45, v[14:15]
	v_mad_i32_i24 v249, v253, s45, v249
	v_lshl_add_u64 v[248:249], v[248:249], 0, s[100:101]
	v_lshl_add_u64 v[248:249], v[248:249], 0, v[250:251]
	global_load_dwordx4 v[240:243], v[248:249], off offset:2048
	global_load_dwordx4 v[244:247], v[248:249], off offset:2304
	v_lshl_add_u64 v[252:253], v[18:19], 0, v[88:89]
	v_mad_u64_u32 v[248:249], s[88:89], v252, s45, v[14:15]
	v_mad_i32_i24 v249, v253, s45, v249
	v_lshl_add_u64 v[248:249], v[248:249], 0, s[100:101]
	v_lshl_add_u64 v[248:249], v[248:249], 0, v[250:251]
	global_load_dwordx4 v[240:243], v[248:249], off offset:2048
	global_load_dwordx4 v[244:247], v[248:249], off offset:2304
	v_lshl_add_u64 v[252:253], v[18:19], 0, v[90:91]
	v_mad_u64_u32 v[248:249], s[88:89], v252, s45, v[14:15]
	v_mad_i32_i24 v249, v253, s45, v249
	v_lshl_add_u64 v[248:249], v[248:249], 0, s[100:101]
	v_lshl_add_u64 v[248:249], v[248:249], 0, v[250:251]
	global_load_dwordx4 v[240:243], v[248:249], off offset:2048
	global_load_dwordx4 v[244:247], v[248:249], off offset:2304
	v_lshl_add_u64 v[252:253], v[18:19], 0, v[92:93]
	v_mad_u64_u32 v[248:249], s[88:89], v252, s45, v[14:15]
	v_mad_i32_i24 v249, v253, s45, v249
	v_lshl_add_u64 v[248:249], v[248:249], 0, s[100:101]
	v_lshl_add_u64 v[248:249], v[248:249], 0, v[250:251]
	global_load_dwordx4 v[240:243], v[248:249], off offset:2048
	global_load_dwordx4 v[244:247], v[248:249], off offset:2304
	s_and_saveexec_b64 s[38:39], s[52:53]
	s_cbranch_execz .LBB0_1062
	v_lshl_add_u64 v[6:7], v[18:19], 0, v[86:87]
	v_mad_u64_u32 v[8:9], s[52:53], v6, s45, v[14:15]
	v_mad_i32_i24 v9, v7, s45, v9
	s_lshl_b32 s28, s51, 1
	v_lshl_add_u64 v[6:7], v[8:9], 0, s[28:29]
	v_mov_b32_e32 v17, v2
	v_lshl_add_u64 v[6:7], v[6:7], 0, v[16:17]
	global_load_dwordx4 v[10:13], v[6:7], off offset:2048
	s_nop 0
	global_load_dwordx4 v[6:9], v[6:7], off offset:2304
